# hyena LST=6/2 FFT passes: per-element LDS address = base ^ 32m (one v_xor instead of bitop3+shift)
# baseline (speedup 1.0000x reference)
; __device__ __forceinline__ cf add_mib(cf a, cf b) { cf r; asm("v_pk_add_f32 %0, %1, %2 op_sel:[0,1] op_sel_hi:[1,0] neg_hi:[0,1]" : "=v"(r) : "v"(a), "v"(b)); return r; }
; template <bool INV, bool HALFIN = false> __device__ __forceinline__ void dft16(cf (&x)[16]) {
; #pragma unroll
;     for (int m2 = 0; m2 < 4; ++m2) {
;         if (HALFIN) { const cf a0 = x[m2], a1 = x[4 + m2]; x[m2] = a0 + a1; x[8 + m2] = a0 - a1; x[4 + m2] = add_mib(a0, a1); x[12 + m2] = add_pib(a0, a1); }
;         else dft4<INV>(x[m2], x[4 + m2], x[8 + m2], x[12 + m2]);
;     }
;     constexpr float C1 = 0.9238795325112867f, S1 = 0.3826834323650898f, C2 = 0.7071067811865476f;
;     x[4 * 1 + 1] = tw16<INV>(x[5], C1, S1);  x[4 * 1 + 2] = tw16<INV>(x[6], C2, C2);   x[4 * 1 + 3] = tw16<INV>(x[7], S1, C1);
;     x[4 * 2 + 1] = tw16<INV>(x[9], C2, C2);  x[4 * 2 + 2] = tw16<INV>(x[10], 0.f, 1.f); x[4 * 2 + 3] = tw16<INV>(x[11], -C2, C2);
;     x[4 * 3 + 1] = tw16<INV>(x[13], S1, C1); x[4 * 3 + 2] = tw16<INV>(x[14], -C2, C2); x[4 * 3 + 3] = tw16<INV>(x[15], -C1, -S1);
; #pragma unroll
;     for (int q1 = 0; q1 < 4; ++q1) dft4<INV>(x[4 * q1], x[4 * q1 + 1], x[4 * q1 + 2], x[4 * q1 + 3]);
; template <bool INV, int LST, bool HALF = false> __device__ __forceinline__ void fft_pass16(LAS cf* z, const LAS cf* Thi, const LAS cf* Tlo, int tid) {
;     ...
;         const int g = tid + 512 * it; const int j0 = g & (st - 1); const int base = ((g >> LST) << (LST + 4)) + j0; const int phb = PH(base);
;         if (LST == 10 || it == 0) {
;             const int e1 = j0 << (10 - LST);
;             w[1] = cmul(Thi[e1 >> 7], Tlo[e1 & 127]);
;             w[2] = cmul(w[1], w[1]); w[3] = cmul(w[2], w[1]); w[4] = cmul(w[2], w[2]); w[5] = cmul(w[4], w[1]); w[6] = cmul(w[3], w[3]); w[7] = cmul(w[4], w[3]); w[8] = cmul(w[4], w[4]);
; #pragma unroll
;             for (int q = 9; q < 16; ++q) w[q] = cmul(w[8], w[q - 8]);
;         }
;         cf x[16];
;         if (!INV) {
; #pragma unroll
;             for (int m = 0; m < 16; ++m) { if (HALF && m >= 8) x[m] = (cf){0.f, 0.f}; else x[m] = z[pass_pos<LST>(base, phb, m)]; }
;             dft16<false, HALF>(x);
; #pragma unroll
;             for (int q = 0; q < 16; ++q) { cf y = x[4 * (q & 3) + (q >> 2)]; if (q) y = cmul(y, w[q]); z[pass_pos<LST>(base, phb, q)] = y; }
.LBB0_1022:
	v_add_u32_e32 v21, s21, v169
	v_and_b32_e32 v21, 0x7c00, v21
	v_or_b32_e32 v29, v21, v122
	v_lshl_add_u32 v29, v29, 3, 0
	s_nop 0
	s_nop 0
	v_xor_b32_e32 v109, 0x80, v29
	s_nop 0
	v_xor_b32_e32 v113, 0x100, v29
	s_nop 0
	s_nop 0
	v_xor_b32_e32 v110, 0xa0, v29
	s_nop 0
	v_xor_b32_e32 v114, 0x120, v29
	s_nop 0
	v_xor_b32_e32 v182, 0x180, v29
	s_nop 0
	s_nop 0
	s_nop 0
	s_nop 0
	v_xor_b32_e32 v111, 0xc0, v29
	s_nop 0
	v_xor_b32_e32 v115, 0x140, v29
	s_nop 0
	v_xor_b32_e32 v183, 0x1a0, v29
	s_nop 0
	s_nop 0
	v_xor_b32_e32 v37, 0x20, v29
	v_xor_b32_e32 v41, 0x40, v29
	v_xor_b32_e32 v108, 0x60, v29
	ds_read_b64 v[70:71], v29
	ds_read_b64 v[72:73], v37 offset:512
	ds_read_b64 v[74:75], v41 offset:1024
	ds_read_b64 v[76:77], v108 offset:1536
	v_xor_b32_e32 v112, 0xe0, v29
	ds_read_b64 v[78:79], v109 offset:2048
	ds_read_b64 v[80:81], v110 offset:2560
	ds_read_b64 v[82:83], v111 offset:3072
	ds_read_b64 v[84:85], v112 offset:3584
	v_xor_b32_e32 v125, 0x160, v29
	ds_read_b64 v[86:87], v113 offset:4096
	ds_read_b64 v[88:89], v114 offset:4608
	ds_read_b64 v[90:91], v115 offset:5120
	ds_read_b64 v[92:93], v125 offset:5632
	v_xor_b32_e32 v216, 0x1c0, v29
	v_xor_b32_e32 v21, 0x1e0, v29
	ds_read_b64 v[94:95], v182 offset:6144
	ds_read_b64 v[96:97], v183 offset:6656
	ds_read_b64 v[98:99], v216 offset:7168
	ds_read_b64 v[100:101], v21 offset:7680
	s_waitcnt lgkmcnt(7)
	v_pk_add_f32 v[102:103], v[70:71], v[86:87]
	v_pk_add_f32 v[70:71], v[70:71], v[86:87] neg_lo:[0,1] neg_hi:[0,1]
	s_waitcnt lgkmcnt(3)
	v_pk_add_f32 v[86:87], v[78:79], v[94:95]
	v_pk_add_f32 v[78:79], v[78:79], v[94:95] neg_lo:[0,1] neg_hi:[0,1]
	v_pk_add_f32 v[94:95], v[102:103], v[86:87]
	v_pk_add_f32 v[86:87], v[102:103], v[86:87] neg_lo:[0,1] neg_hi:[0,1]
	v_pk_add_f32 v[102:103], v[70:71], v[78:79] op_sel:[0,1] op_sel_hi:[1,0] neg_hi:[0,1]
	v_pk_add_f32 v[70:71], v[70:71], v[78:79] op_sel:[0,1] op_sel_hi:[1,0] neg_lo:[0,1]
	v_pk_add_f32 v[78:79], v[72:73], v[88:89]
	v_pk_add_f32 v[72:73], v[72:73], v[88:89] neg_lo:[0,1] neg_hi:[0,1]
	s_waitcnt lgkmcnt(2)
	v_pk_add_f32 v[88:89], v[80:81], v[96:97]
	v_pk_add_f32 v[80:81], v[80:81], v[96:97] neg_lo:[0,1] neg_hi:[0,1]
	v_pk_add_f32 v[96:97], v[78:79], v[88:89]
	v_pk_add_f32 v[78:79], v[78:79], v[88:89] neg_lo:[0,1] neg_hi:[0,1]
	v_pk_add_f32 v[88:89], v[72:73], v[80:81] op_sel:[0,1] op_sel_hi:[1,0] neg_hi:[0,1]
	v_pk_add_f32 v[72:73], v[72:73], v[80:81] op_sel:[0,1] op_sel_hi:[1,0] neg_lo:[0,1]
	v_pk_add_f32 v[80:81], v[74:75], v[90:91]
	v_pk_add_f32 v[74:75], v[74:75], v[90:91] neg_lo:[0,1] neg_hi:[0,1]
	s_waitcnt lgkmcnt(1)
	v_pk_add_f32 v[90:91], v[82:83], v[98:99]
	v_pk_add_f32 v[82:83], v[82:83], v[98:99] neg_lo:[0,1] neg_hi:[0,1]
	v_pk_add_f32 v[98:99], v[80:81], v[90:91]
	v_pk_add_f32 v[80:81], v[80:81], v[90:91] neg_lo:[0,1] neg_hi:[0,1]
	v_pk_add_f32 v[90:91], v[74:75], v[82:83] op_sel:[0,1] op_sel_hi:[1,0] neg_hi:[0,1]
	v_pk_add_f32 v[74:75], v[74:75], v[82:83] op_sel:[0,1] op_sel_hi:[1,0] neg_lo:[0,1]
	v_pk_add_f32 v[82:83], v[76:77], v[92:93]
	v_pk_add_f32 v[76:77], v[76:77], v[92:93] neg_lo:[0,1] neg_hi:[0,1]
	s_waitcnt lgkmcnt(0)
	v_pk_add_f32 v[92:93], v[84:85], v[100:101]
	v_pk_add_f32 v[84:85], v[84:85], v[100:101] neg_lo:[0,1] neg_hi:[0,1]
	v_pk_add_f32 v[100:101], v[82:83], v[92:93]
	v_pk_add_f32 v[82:83], v[82:83], v[92:93] neg_lo:[0,1] neg_hi:[0,1]
	v_pk_add_f32 v[92:93], v[76:77], v[84:85] op_sel:[0,1] op_sel_hi:[1,0] neg_hi:[0,1]
	v_pk_add_f32 v[76:77], v[76:77], v[84:85] op_sel:[0,1] op_sel_hi:[1,0] neg_lo:[0,1]
	v_pk_mul_f32 v[84:85], v[88:89], s[22:23] op_sel_hi:[1,0]
	s_mov_b32 s48, s37
	v_pk_fma_f32 v[104:105], v[88:89], s[20:21], v[84:85] op_sel:[0,0,1] op_sel_hi:[1,0,0]
	v_pk_fma_f32 v[84:85], v[88:89], s[20:21], v[84:85] op_sel:[0,0,1] op_sel_hi:[1,0,0] neg_lo:[0,0,1] neg_hi:[0,0,1]
	s_mov_b32 s49, s22
	v_mov_b32_e32 v105, v85
	v_pk_mul_f32 v[84:85], v[90:91], s[24:25] op_sel_hi:[1,0]
	s_andn2_b64 vcc, exec, s[46:47]
	v_pk_fma_f32 v[88:89], v[90:91], s[24:25], v[84:85] op_sel:[0,0,1] op_sel_hi:[1,0,0]
	v_pk_fma_f32 v[84:85], v[90:91], s[24:25], v[84:85] op_sel_hi:[1,0,0] neg_lo:[0,0,1] neg_hi:[0,0,1]
	v_pk_mul_f32 v[90:91], v[92:93], s[20:21] op_sel_hi:[1,0]
	v_mov_b32_e32 v89, v85
	v_pk_fma_f32 v[106:107], v[92:93], s[22:23], v[90:91] op_sel:[0,0,1] op_sel_hi:[1,0,0]
	v_pk_fma_f32 v[90:91], v[92:93], s[22:23], v[90:91] op_sel:[0,0,1] op_sel_hi:[1,0,0] neg_lo:[0,0,1] neg_hi:[0,0,1]
	v_pk_add_f32 v[84:85], v[102:103], v[88:89]
	v_mov_b32_e32 v107, v91
	v_pk_mul_f32 v[90:91], v[78:79], s[24:25] op_sel_hi:[1,0]
	v_pk_add_f32 v[88:89], v[102:103], v[88:89] neg_lo:[0,1] neg_hi:[0,1]
	v_pk_fma_f32 v[92:93], v[78:79], s[24:25], v[90:91] op_sel:[0,0,1] op_sel_hi:[1,0,0]
	v_pk_fma_f32 v[78:79], v[78:79], s[24:25], v[90:91] op_sel_hi:[1,0,0] neg_lo:[0,0,1] neg_hi:[0,0,1]
	v_pk_add_f32 v[102:103], v[104:105], v[106:107] neg_lo:[0,1] neg_hi:[0,1]
	v_mov_b32_e32 v93, v79
	v_pk_fma_f32 v[78:79], v[80:81], 0, v[80:81] op_sel:[0,0,1] op_sel_hi:[1,0,0]
	v_pk_fma_f32 v[80:81], v[80:81], 0, v[80:81] op_sel:[0,0,1] op_sel_hi:[1,0,0] neg_lo:[0,0,1] neg_hi:[0,0,1]
	s_mov_b64 s[46:47], 0
	v_mul_f32_e32 v80, 0x3f3504f3, v82
	v_mov_b32_e32 v79, v81
	v_pk_fma_f32 v[80:81], v[82:83], s[24:25], v[80:81] op_sel:[1,0,0] op_sel_hi:[1,1,0] neg_lo:[0,0,1] neg_hi:[0,0,1]
	v_pk_mul_f32 v[82:83], v[72:73], s[20:21] op_sel_hi:[1,0]
	s_movk_i32 s21, 0x2000
	v_pk_fma_f32 v[90:91], v[72:73], s[22:23], v[82:83] op_sel:[0,0,1] op_sel_hi:[1,0,0]
	v_pk_fma_f32 v[72:73], v[72:73], s[22:23], v[82:83] op_sel:[0,0,1] op_sel_hi:[1,0,0] neg_lo:[0,0,1] neg_hi:[0,0,1]
; template <bool INV, bool HALFIN = false> __device__ __forceinline__ void dft16(cf (&x)[16]) {
;     ...
;     for (int q1 = 0; q1 < 4; ++q1) dft4<INV>(x[4 * q1], x[4 * q1 + 1], x[4 * q1 + 2], x[4 * q1 + 3]);
; template <bool INV, int LST, bool HALF = false> __device__ __forceinline__ void fft_pass16(LAS cf* z, const LAS cf* Thi, const LAS cf* Tlo, int tid) {
;     ...
;             for (int q = 0; q < 16; ++q) { cf y = x[4 * (q & 3) + (q >> 2)]; if (q) y = cmul(y, w[q]); z[pass_pos<LST>(base, phb, q)] = y; }
	v_pk_add_f32 v[82:83], v[94:95], v[98:99] neg_lo:[0,1] neg_hi:[0,1]
	v_mul_f32_e32 v72, 0x3f3504f3, v74
	v_mov_b32_e32 v91, v73
	v_pk_fma_f32 v[72:73], v[74:75], s[24:25], v[72:73] op_sel:[1,0,0] op_sel_hi:[1,1,0] neg_lo:[0,0,1] neg_hi:[0,0,1]
	v_pk_mul_f32 v[74:75], v[76:77], s[36:37] op_sel:[1,0]
	s_nop 0
	v_pk_fma_f32 v[74:75], v[76:77], s[48:49], v[74:75] op_sel_hi:[0,1,1]
	v_pk_add_f32 v[76:77], v[94:95], v[98:99]
	v_pk_add_f32 v[94:95], v[96:97], v[100:101]
	v_pk_add_f32 v[96:97], v[96:97], v[100:101] neg_lo:[0,1] neg_hi:[0,1]
	v_pk_add_f32 v[98:99], v[76:77], v[94:95] neg_lo:[0,1] neg_hi:[0,1]
	v_pk_add_f32 v[100:101], v[82:83], v[96:97] op_sel:[0,1] op_sel_hi:[1,0] neg_hi:[0,1]
	v_pk_add_f32 v[82:83], v[82:83], v[96:97] op_sel:[0,1] op_sel_hi:[1,0] neg_lo:[0,1]
	v_pk_add_f32 v[96:97], v[104:105], v[106:107]
	s_nop 0
	v_pk_add_f32 v[104:105], v[84:85], v[96:97]
	v_pk_add_f32 v[84:85], v[84:85], v[96:97] neg_lo:[0,1] neg_hi:[0,1]
	v_pk_add_f32 v[96:97], v[88:89], v[102:103] op_sel:[0,1] op_sel_hi:[1,0] neg_hi:[0,1]
	v_pk_add_f32 v[88:89], v[88:89], v[102:103] op_sel:[0,1] op_sel_hi:[1,0] neg_lo:[0,1]
	v_pk_add_f32 v[102:103], v[86:87], v[78:79]
	v_pk_add_f32 v[78:79], v[86:87], v[78:79] neg_lo:[0,1] neg_hi:[0,1]
	v_pk_add_f32 v[86:87], v[92:93], v[80:81]
	v_pk_add_f32 v[80:81], v[92:93], v[80:81] neg_lo:[0,1] neg_hi:[0,1]
	v_pk_add_f32 v[92:93], v[102:103], v[86:87]
	v_pk_add_f32 v[86:87], v[102:103], v[86:87] neg_lo:[0,1] neg_hi:[0,1]
	v_pk_add_f32 v[102:103], v[78:79], v[80:81] op_sel:[0,1] op_sel_hi:[1,0] neg_hi:[0,1]
	v_pk_add_f32 v[78:79], v[78:79], v[80:81] op_sel:[0,1] op_sel_hi:[1,0] neg_lo:[0,1]
	v_pk_add_f32 v[80:81], v[70:71], v[72:73]
	v_pk_add_f32 v[70:71], v[70:71], v[72:73] neg_lo:[0,1] neg_hi:[0,1]
	v_pk_add_f32 v[72:73], v[90:91], v[74:75]
	v_pk_add_f32 v[74:75], v[90:91], v[74:75] neg_lo:[0,1] neg_hi:[0,1]
	v_pk_add_f32 v[90:91], v[80:81], v[72:73]
	v_pk_add_f32 v[72:73], v[80:81], v[72:73] neg_lo:[0,1] neg_hi:[0,1]
	v_pk_add_f32 v[80:81], v[70:71], v[74:75] op_sel:[0,1] op_sel_hi:[1,0] neg_hi:[0,1]
	v_pk_add_f32 v[70:71], v[70:71], v[74:75] op_sel:[0,1] op_sel_hi:[1,0] neg_lo:[0,1]
	v_pk_add_f32 v[74:75], v[76:77], v[94:95]
	ds_write_b64 v29, v[74:75]
	v_pk_mul_f32 v[74:75], v[104:105], v[22:23] op_sel:[0,0] op_sel_hi:[0,1]
	s_nop 0
	v_pk_fma_f32 v[74:75], v[104:105], v[22:23], v[74:75] op_sel:[1,1,0] op_sel_hi:[1,0,1] neg_lo:[1,0,0]
	ds_write_b64 v37, v[74:75] offset:512
	v_pk_mul_f32 v[74:75], v[92:93], v[30:31] op_sel:[0,0] op_sel_hi:[0,1]
	s_nop 0
	v_pk_fma_f32 v[74:75], v[92:93], v[30:31], v[74:75] op_sel:[1,1,0] op_sel_hi:[1,0,1] neg_lo:[1,0,0]
	ds_write_b64 v41, v[74:75] offset:1024
	v_pk_mul_f32 v[74:75], v[90:91], v[38:39] op_sel:[0,0] op_sel_hi:[0,1]
	s_nop 0
	v_pk_fma_f32 v[74:75], v[90:91], v[38:39], v[74:75] op_sel:[1,1,0] op_sel_hi:[1,0,1] neg_lo:[1,0,0]
	ds_write_b64 v108, v[74:75] offset:1536
	v_pk_mul_f32 v[74:75], v[100:101], v[42:43] op_sel:[0,0] op_sel_hi:[0,1]
	s_nop 0
	v_pk_fma_f32 v[74:75], v[100:101], v[42:43], v[74:75] op_sel:[1,1,0] op_sel_hi:[1,0,1] neg_lo:[1,0,0]
	ds_write_b64 v109, v[74:75] offset:2048
	v_pk_mul_f32 v[74:75], v[96:97], v[48:49] op_sel:[0,0] op_sel_hi:[0,1]
	s_nop 0
	v_pk_fma_f32 v[74:75], v[96:97], v[48:49], v[74:75] op_sel:[1,1,0] op_sel_hi:[1,0,1] neg_lo:[1,0,0]
	ds_write_b64 v110, v[74:75] offset:2560
	v_pk_mul_f32 v[74:75], v[102:103], v[50:51] op_sel:[0,0] op_sel_hi:[0,1]
	s_nop 0
	v_pk_fma_f32 v[74:75], v[102:103], v[50:51], v[74:75] op_sel:[1,1,0] op_sel_hi:[1,0,1] neg_lo:[1,0,0]
	ds_write_b64 v111, v[74:75] offset:3072
	v_pk_mul_f32 v[74:75], v[80:81], v[52:53] op_sel:[0,0] op_sel_hi:[0,1]
	s_nop 0
	v_pk_fma_f32 v[74:75], v[80:81], v[52:53], v[74:75] op_sel:[1,1,0] op_sel_hi:[1,0,1] neg_lo:[1,0,0]
	ds_write_b64 v112, v[74:75] offset:3584
	v_pk_mul_f32 v[74:75], v[98:99], v[54:55] op_sel:[0,0] op_sel_hi:[0,1]
	s_nop 0
	v_pk_fma_f32 v[74:75], v[98:99], v[54:55], v[74:75] op_sel:[1,1,0] op_sel_hi:[1,0,1] neg_lo:[1,0,0]
	ds_write_b64 v113, v[74:75] offset:4096
	v_pk_mul_f32 v[74:75], v[84:85], v[56:57] op_sel:[0,0] op_sel_hi:[0,1]
	s_nop 0
	v_pk_fma_f32 v[74:75], v[84:85], v[56:57], v[74:75] op_sel:[1,1,0] op_sel_hi:[1,0,1] neg_lo:[1,0,0]
	ds_write_b64 v114, v[74:75] offset:4608
	v_pk_mul_f32 v[74:75], v[86:87], v[58:59] op_sel:[0,0] op_sel_hi:[0,1]
	s_nop 0
	v_pk_fma_f32 v[74:75], v[86:87], v[58:59], v[74:75] op_sel:[1,1,0] op_sel_hi:[1,0,1] neg_lo:[1,0,0]
	ds_write_b64 v115, v[74:75] offset:5120
	v_pk_mul_f32 v[74:75], v[72:73], v[60:61] op_sel:[0,0] op_sel_hi:[0,1]
	s_nop 0
	v_pk_fma_f32 v[72:73], v[72:73], v[60:61], v[74:75] op_sel:[1,1,0] op_sel_hi:[1,0,1] neg_lo:[1,0,0]
	ds_write_b64 v125, v[72:73] offset:5632
	v_pk_mul_f32 v[72:73], v[82:83], v[62:63] op_sel:[0,0] op_sel_hi:[0,1]
	s_nop 0
	v_pk_fma_f32 v[72:73], v[82:83], v[62:63], v[72:73] op_sel:[1,1,0] op_sel_hi:[1,0,1] neg_lo:[1,0,0]
	ds_write_b64 v182, v[72:73] offset:6144
	v_pk_mul_f32 v[72:73], v[88:89], v[64:65] op_sel:[0,0] op_sel_hi:[0,1]
	s_nop 0
	v_pk_fma_f32 v[72:73], v[88:89], v[64:65], v[72:73] op_sel:[1,1,0] op_sel_hi:[1,0,1] neg_lo:[1,0,0]
	ds_write_b64 v183, v[72:73] offset:6656
	v_pk_mul_f32 v[72:73], v[78:79], v[66:67] op_sel:[0,0] op_sel_hi:[0,1]
	s_nop 0
	v_pk_fma_f32 v[72:73], v[78:79], v[66:67], v[72:73] op_sel:[1,1,0] op_sel_hi:[1,0,1] neg_lo:[1,0,0]
	ds_write_b64 v216, v[72:73] offset:7168
	v_pk_mul_f32 v[72:73], v[70:71], v[68:69] op_sel:[0,0] op_sel_hi:[0,1]
	s_nop 0
	v_pk_fma_f32 v[70:71], v[70:71], v[68:69], v[72:73] op_sel:[1,1,0] op_sel_hi:[1,0,1] neg_lo:[1,0,0]
	ds_write_b64 v21, v[70:71] offset:7680
	s_cbranch_vccz .LBB0_1025

; __device__ __forceinline__ cf add_mib(cf a, cf b) { cf r; asm("v_pk_add_f32 %0, %1, %2 op_sel:[0,1] op_sel_hi:[1,0] neg_hi:[0,1]" : "=v"(r) : "v"(a), "v"(b)); return r; }
; template <bool INV, bool HALFIN = false> __device__ __forceinline__ void dft16(cf (&x)[16]) {
; #pragma unroll
;     for (int m2 = 0; m2 < 4; ++m2) {
;         if (HALFIN) { const cf a0 = x[m2], a1 = x[4 + m2]; x[m2] = a0 + a1; x[8 + m2] = a0 - a1; x[4 + m2] = add_mib(a0, a1); x[12 + m2] = add_pib(a0, a1); }
;         else dft4<INV>(x[m2], x[4 + m2], x[8 + m2], x[12 + m2]);
;     }
;     constexpr float C1 = 0.9238795325112867f, S1 = 0.3826834323650898f, C2 = 0.7071067811865476f;
;     x[4 * 1 + 1] = tw16<INV>(x[5], C1, S1);  x[4 * 1 + 2] = tw16<INV>(x[6], C2, C2);   x[4 * 1 + 3] = tw16<INV>(x[7], S1, C1);
;     x[4 * 2 + 1] = tw16<INV>(x[9], C2, C2);  x[4 * 2 + 2] = tw16<INV>(x[10], 0.f, 1.f); x[4 * 2 + 3] = tw16<INV>(x[11], -C2, C2);
;     x[4 * 3 + 1] = tw16<INV>(x[13], S1, C1); x[4 * 3 + 2] = tw16<INV>(x[14], -C2, C2); x[4 * 3 + 3] = tw16<INV>(x[15], -C1, -S1);
; #pragma unroll
;     for (int q1 = 0; q1 < 4; ++q1) dft4<INV>(x[4 * q1], x[4 * q1 + 1], x[4 * q1 + 2], x[4 * q1 + 3]);
; template <bool INV, int LST, bool HALF = false> __device__ __forceinline__ void fft_pass16(LAS cf* z, const LAS cf* Thi, const LAS cf* Tlo, int tid) {
;     ...
;         const int g = tid + 512 * it; const int j0 = g & (st - 1); const int base = ((g >> LST) << (LST + 4)) + j0; const int phb = PH(base);
;         if (LST == 10 || it == 0) {
;             const int e1 = j0 << (10 - LST);
;             w[1] = cmul(Thi[e1 >> 7], Tlo[e1 & 127]);
;             w[2] = cmul(w[1], w[1]); w[3] = cmul(w[2], w[1]); w[4] = cmul(w[2], w[2]); w[5] = cmul(w[4], w[1]); w[6] = cmul(w[3], w[3]); w[7] = cmul(w[4], w[3]); w[8] = cmul(w[4], w[4]);
; #pragma unroll
;             for (int q = 9; q < 16; ++q) w[q] = cmul(w[8], w[q - 8]);
;         }
;         cf x[16];
;         if (!INV) {
; #pragma unroll
;             for (int m = 0; m < 16; ++m) { if (HALF && m >= 8) x[m] = (cf){0.f, 0.f}; else x[m] = z[pass_pos<LST>(base, phb, m)]; }
;             dft16<false, HALF>(x);
; #pragma unroll
;             for (int q = 0; q < 16; ++q) { cf y = x[4 * (q & 3) + (q >> 2)]; if (q) y = cmul(y, w[q]); z[pass_pos<LST>(base, phb, q)] = y; }
.LBB0_1026:
	v_add_u32_e32 v29, s21, v169
	v_and_or_b32 v29, v29, s71, v172
	v_lshl_add_u32 v37, v29, 3, v174
	s_nop 0
	s_nop 0
	v_xor_b32_e32 v110, 0x80, v37
	s_nop 0
	v_xor_b32_e32 v114, 0x100, v37
	s_nop 0
	s_nop 0
	s_nop 0
	v_xor_b32_e32 v111, 0xa0, v37
	s_nop 0
	v_xor_b32_e32 v115, 0x120, v37
	s_nop 0
	v_xor_b32_e32 v183, 0x180, v37
	s_nop 0
	s_nop 0
	v_xor_b32_e32 v108, 0x40, v37
	s_nop 0
	v_xor_b32_e32 v112, 0xc0, v37
	s_nop 0
	v_xor_b32_e32 v125, 0x140, v37
	s_nop 0
	v_xor_b32_e32 v216, 0x1a0, v37
	s_nop 0
	s_nop 0
	v_xor_b32_e32 v41, 0x20, v37
	v_xor_b32_e32 v109, 0x60, v37
	ds_read_b64 v[70:71], v37
	ds_read_b64 v[72:73], v41
	ds_read_b64 v[74:75], v108
	ds_read_b64 v[76:77], v109
	v_xor_b32_e32 v113, 0xe0, v37
	ds_read_b64 v[78:79], v110
	ds_read_b64 v[80:81], v111
	ds_read_b64 v[82:83], v112
	ds_read_b64 v[84:85], v113
	v_xor_b32_e32 v182, 0x160, v37
	ds_read_b64 v[86:87], v114
	ds_read_b64 v[88:89], v115
	ds_read_b64 v[90:91], v125
	ds_read_b64 v[92:93], v182
	v_xor_b32_e32 v217, 0x1c0, v37
	v_xor_b32_e32 v29, 0x1e0, v37
	ds_read_b64 v[94:95], v183
	ds_read_b64 v[96:97], v216
	ds_read_b64 v[98:99], v217
	ds_read_b64 v[100:101], v29
	s_waitcnt lgkmcnt(7)
	v_pk_add_f32 v[102:103], v[70:71], v[86:87]
	v_pk_add_f32 v[70:71], v[70:71], v[86:87] neg_lo:[0,1] neg_hi:[0,1]
	s_waitcnt lgkmcnt(3)
	v_pk_add_f32 v[86:87], v[78:79], v[94:95]
	v_pk_add_f32 v[78:79], v[78:79], v[94:95] neg_lo:[0,1] neg_hi:[0,1]
	v_pk_add_f32 v[94:95], v[102:103], v[86:87]
	v_pk_add_f32 v[86:87], v[102:103], v[86:87] neg_lo:[0,1] neg_hi:[0,1]
	v_pk_add_f32 v[102:103], v[70:71], v[78:79] op_sel:[0,1] op_sel_hi:[1,0] neg_hi:[0,1]
	v_pk_add_f32 v[70:71], v[70:71], v[78:79] op_sel:[0,1] op_sel_hi:[1,0] neg_lo:[0,1]
	v_pk_add_f32 v[78:79], v[72:73], v[88:89]
	v_pk_add_f32 v[72:73], v[72:73], v[88:89] neg_lo:[0,1] neg_hi:[0,1]
	s_waitcnt lgkmcnt(2)
	v_pk_add_f32 v[88:89], v[80:81], v[96:97]
	v_pk_add_f32 v[80:81], v[80:81], v[96:97] neg_lo:[0,1] neg_hi:[0,1]
	v_pk_add_f32 v[96:97], v[78:79], v[88:89]
	v_pk_add_f32 v[78:79], v[78:79], v[88:89] neg_lo:[0,1] neg_hi:[0,1]
	v_pk_add_f32 v[88:89], v[72:73], v[80:81] op_sel:[0,1] op_sel_hi:[1,0] neg_hi:[0,1]
	v_pk_add_f32 v[72:73], v[72:73], v[80:81] op_sel:[0,1] op_sel_hi:[1,0] neg_lo:[0,1]
	v_pk_add_f32 v[80:81], v[74:75], v[90:91]
	v_pk_add_f32 v[74:75], v[74:75], v[90:91] neg_lo:[0,1] neg_hi:[0,1]
	s_waitcnt lgkmcnt(1)
	v_pk_add_f32 v[90:91], v[82:83], v[98:99]
	v_pk_add_f32 v[82:83], v[82:83], v[98:99] neg_lo:[0,1] neg_hi:[0,1]
	v_pk_add_f32 v[98:99], v[80:81], v[90:91]
	v_pk_add_f32 v[80:81], v[80:81], v[90:91] neg_lo:[0,1] neg_hi:[0,1]
	v_pk_add_f32 v[90:91], v[74:75], v[82:83] op_sel:[0,1] op_sel_hi:[1,0] neg_hi:[0,1]
	v_pk_add_f32 v[74:75], v[74:75], v[82:83] op_sel:[0,1] op_sel_hi:[1,0] neg_lo:[0,1]
	v_pk_add_f32 v[82:83], v[76:77], v[92:93]
	v_pk_add_f32 v[76:77], v[76:77], v[92:93] neg_lo:[0,1] neg_hi:[0,1]
	s_waitcnt lgkmcnt(0)
	v_pk_add_f32 v[92:93], v[84:85], v[100:101]
	v_pk_add_f32 v[84:85], v[84:85], v[100:101] neg_lo:[0,1] neg_hi:[0,1]
	v_pk_add_f32 v[100:101], v[82:83], v[92:93]
	v_pk_add_f32 v[82:83], v[82:83], v[92:93] neg_lo:[0,1] neg_hi:[0,1]
	v_pk_add_f32 v[92:93], v[76:77], v[84:85] op_sel:[0,1] op_sel_hi:[1,0] neg_hi:[0,1]
	v_pk_add_f32 v[76:77], v[76:77], v[84:85] op_sel:[0,1] op_sel_hi:[1,0] neg_lo:[0,1]
	v_pk_mul_f32 v[84:85], v[88:89], s[22:23] op_sel_hi:[1,0]
	s_mov_b32 s48, s37
	v_pk_fma_f32 v[104:105], v[88:89], s[20:21], v[84:85] op_sel:[0,0,1] op_sel_hi:[1,0,0]
	v_pk_fma_f32 v[84:85], v[88:89], s[20:21], v[84:85] op_sel:[0,0,1] op_sel_hi:[1,0,0] neg_lo:[0,0,1] neg_hi:[0,0,1]
	s_mov_b32 s49, s22
	v_mov_b32_e32 v105, v85
	v_pk_mul_f32 v[84:85], v[90:91], s[24:25] op_sel_hi:[1,0]
	s_andn2_b64 vcc, exec, s[46:47]
	v_pk_fma_f32 v[88:89], v[90:91], s[24:25], v[84:85] op_sel:[0,0,1] op_sel_hi:[1,0,0]
	v_pk_fma_f32 v[84:85], v[90:91], s[24:25], v[84:85] op_sel_hi:[1,0,0] neg_lo:[0,0,1] neg_hi:[0,0,1]
	v_pk_mul_f32 v[90:91], v[92:93], s[20:21] op_sel_hi:[1,0]
	v_mov_b32_e32 v89, v85
	v_pk_fma_f32 v[106:107], v[92:93], s[22:23], v[90:91] op_sel:[0,0,1] op_sel_hi:[1,0,0]
	v_pk_fma_f32 v[90:91], v[92:93], s[22:23], v[90:91] op_sel:[0,0,1] op_sel_hi:[1,0,0] neg_lo:[0,0,1] neg_hi:[0,0,1]
	v_pk_add_f32 v[84:85], v[102:103], v[88:89]
	v_mov_b32_e32 v107, v91
	v_pk_mul_f32 v[90:91], v[78:79], s[24:25] op_sel_hi:[1,0]
	v_pk_add_f32 v[88:89], v[102:103], v[88:89] neg_lo:[0,1] neg_hi:[0,1]
	v_pk_fma_f32 v[92:93], v[78:79], s[24:25], v[90:91] op_sel:[0,0,1] op_sel_hi:[1,0,0]
	v_pk_fma_f32 v[78:79], v[78:79], s[24:25], v[90:91] op_sel_hi:[1,0,0] neg_lo:[0,0,1] neg_hi:[0,0,1]
	v_pk_add_f32 v[102:103], v[104:105], v[106:107] neg_lo:[0,1] neg_hi:[0,1]
	v_mov_b32_e32 v93, v79
	v_pk_fma_f32 v[78:79], v[80:81], 0, v[80:81] op_sel:[0,0,1] op_sel_hi:[1,0,0]
	v_pk_fma_f32 v[80:81], v[80:81], 0, v[80:81] op_sel:[0,0,1] op_sel_hi:[1,0,0] neg_lo:[0,0,1] neg_hi:[0,0,1]
	s_mov_b64 s[46:47], 0
	v_mul_f32_e32 v80, 0x3f3504f3, v82
	v_mov_b32_e32 v79, v81
	v_pk_fma_f32 v[80:81], v[82:83], s[24:25], v[80:81] op_sel:[1,0,0] op_sel_hi:[1,1,0] neg_lo:[0,0,1] neg_hi:[0,0,1]
	v_pk_mul_f32 v[82:83], v[72:73], s[20:21] op_sel_hi:[1,0]
	s_movk_i32 s21, 0x2000
	v_pk_fma_f32 v[90:91], v[72:73], s[22:23], v[82:83] op_sel:[0,0,1] op_sel_hi:[1,0,0]
	v_pk_fma_f32 v[72:73], v[72:73], s[22:23], v[82:83] op_sel:[0,0,1] op_sel_hi:[1,0,0] neg_lo:[0,0,1] neg_hi:[0,0,1]
; template <bool INV, bool HALFIN = false> __device__ __forceinline__ void dft16(cf (&x)[16]) {
;     ...
;     for (int q1 = 0; q1 < 4; ++q1) dft4<INV>(x[4 * q1], x[4 * q1 + 1], x[4 * q1 + 2], x[4 * q1 + 3]);
; template <bool INV, int LST, bool HALF = false> __device__ __forceinline__ void fft_pass16(LAS cf* z, const LAS cf* Thi, const LAS cf* Tlo, int tid) {
;     ...
;             for (int q = 0; q < 16; ++q) { cf y = x[4 * (q & 3) + (q >> 2)]; if (q) y = cmul(y, w[q]); z[pass_pos<LST>(base, phb, q)] = y; }
	v_pk_add_f32 v[82:83], v[94:95], v[98:99] neg_lo:[0,1] neg_hi:[0,1]
	v_mul_f32_e32 v72, 0x3f3504f3, v74
	v_mov_b32_e32 v91, v73
	v_pk_fma_f32 v[72:73], v[74:75], s[24:25], v[72:73] op_sel:[1,0,0] op_sel_hi:[1,1,0] neg_lo:[0,0,1] neg_hi:[0,0,1]
	v_pk_mul_f32 v[74:75], v[76:77], s[36:37] op_sel:[1,0]
	s_nop 0
	v_pk_fma_f32 v[74:75], v[76:77], s[48:49], v[74:75] op_sel_hi:[0,1,1]
	v_pk_add_f32 v[76:77], v[94:95], v[98:99]
	v_pk_add_f32 v[94:95], v[96:97], v[100:101]
	v_pk_add_f32 v[96:97], v[96:97], v[100:101] neg_lo:[0,1] neg_hi:[0,1]
	v_pk_add_f32 v[98:99], v[76:77], v[94:95] neg_lo:[0,1] neg_hi:[0,1]
	v_pk_add_f32 v[100:101], v[82:83], v[96:97] op_sel:[0,1] op_sel_hi:[1,0] neg_hi:[0,1]
	v_pk_add_f32 v[82:83], v[82:83], v[96:97] op_sel:[0,1] op_sel_hi:[1,0] neg_lo:[0,1]
	v_pk_add_f32 v[96:97], v[104:105], v[106:107]
	s_nop 0
	v_pk_add_f32 v[104:105], v[84:85], v[96:97]
	v_pk_add_f32 v[84:85], v[84:85], v[96:97] neg_lo:[0,1] neg_hi:[0,1]
	v_pk_add_f32 v[96:97], v[88:89], v[102:103] op_sel:[0,1] op_sel_hi:[1,0] neg_hi:[0,1]
	v_pk_add_f32 v[88:89], v[88:89], v[102:103] op_sel:[0,1] op_sel_hi:[1,0] neg_lo:[0,1]
	v_pk_add_f32 v[102:103], v[86:87], v[78:79]
	v_pk_add_f32 v[78:79], v[86:87], v[78:79] neg_lo:[0,1] neg_hi:[0,1]
	v_pk_add_f32 v[86:87], v[92:93], v[80:81]
	v_pk_add_f32 v[80:81], v[92:93], v[80:81] neg_lo:[0,1] neg_hi:[0,1]
	v_pk_add_f32 v[92:93], v[102:103], v[86:87]
	v_pk_add_f32 v[86:87], v[102:103], v[86:87] neg_lo:[0,1] neg_hi:[0,1]
	v_pk_add_f32 v[102:103], v[78:79], v[80:81] op_sel:[0,1] op_sel_hi:[1,0] neg_hi:[0,1]
	v_pk_add_f32 v[78:79], v[78:79], v[80:81] op_sel:[0,1] op_sel_hi:[1,0] neg_lo:[0,1]
	v_pk_add_f32 v[80:81], v[70:71], v[72:73]
	v_pk_add_f32 v[70:71], v[70:71], v[72:73] neg_lo:[0,1] neg_hi:[0,1]
	v_pk_add_f32 v[72:73], v[90:91], v[74:75]
	v_pk_add_f32 v[74:75], v[90:91], v[74:75] neg_lo:[0,1] neg_hi:[0,1]
	v_pk_add_f32 v[90:91], v[80:81], v[72:73]
	v_pk_add_f32 v[72:73], v[80:81], v[72:73] neg_lo:[0,1] neg_hi:[0,1]
	v_pk_add_f32 v[80:81], v[70:71], v[74:75] op_sel:[0,1] op_sel_hi:[1,0] neg_hi:[0,1]
	v_pk_add_f32 v[70:71], v[70:71], v[74:75] op_sel:[0,1] op_sel_hi:[1,0] neg_lo:[0,1]
	v_pk_add_f32 v[74:75], v[76:77], v[94:95]
	ds_write_b64 v37, v[74:75]
	v_pk_mul_f32 v[74:75], v[104:105], v[22:23] op_sel:[0,0] op_sel_hi:[0,1]
	s_nop 0
	v_pk_fma_f32 v[74:75], v[104:105], v[22:23], v[74:75] op_sel:[1,1,0] op_sel_hi:[1,0,1] neg_lo:[1,0,0]
	ds_write_b64 v41, v[74:75]
	v_pk_mul_f32 v[74:75], v[92:93], v[30:31] op_sel:[0,0] op_sel_hi:[0,1]
	s_nop 0
	v_pk_fma_f32 v[74:75], v[92:93], v[30:31], v[74:75] op_sel:[1,1,0] op_sel_hi:[1,0,1] neg_lo:[1,0,0]
	ds_write_b64 v108, v[74:75]
	v_pk_mul_f32 v[74:75], v[90:91], v[38:39] op_sel:[0,0] op_sel_hi:[0,1]
	s_nop 0
	v_pk_fma_f32 v[74:75], v[90:91], v[38:39], v[74:75] op_sel:[1,1,0] op_sel_hi:[1,0,1] neg_lo:[1,0,0]
	ds_write_b64 v109, v[74:75]
	v_pk_mul_f32 v[74:75], v[100:101], v[42:43] op_sel:[0,0] op_sel_hi:[0,1]
	s_nop 0
	v_pk_fma_f32 v[74:75], v[100:101], v[42:43], v[74:75] op_sel:[1,1,0] op_sel_hi:[1,0,1] neg_lo:[1,0,0]
	ds_write_b64 v110, v[74:75]
	v_pk_mul_f32 v[74:75], v[96:97], v[48:49] op_sel:[0,0] op_sel_hi:[0,1]
	s_nop 0
	v_pk_fma_f32 v[74:75], v[96:97], v[48:49], v[74:75] op_sel:[1,1,0] op_sel_hi:[1,0,1] neg_lo:[1,0,0]
	ds_write_b64 v111, v[74:75]
	v_pk_mul_f32 v[74:75], v[102:103], v[50:51] op_sel:[0,0] op_sel_hi:[0,1]
	s_nop 0
	v_pk_fma_f32 v[74:75], v[102:103], v[50:51], v[74:75] op_sel:[1,1,0] op_sel_hi:[1,0,1] neg_lo:[1,0,0]
	ds_write_b64 v112, v[74:75]
	v_pk_mul_f32 v[74:75], v[80:81], v[52:53] op_sel:[0,0] op_sel_hi:[0,1]
	s_nop 0
	v_pk_fma_f32 v[74:75], v[80:81], v[52:53], v[74:75] op_sel:[1,1,0] op_sel_hi:[1,0,1] neg_lo:[1,0,0]
	ds_write_b64 v113, v[74:75]
	v_pk_mul_f32 v[74:75], v[98:99], v[54:55] op_sel:[0,0] op_sel_hi:[0,1]
	s_nop 0
	v_pk_fma_f32 v[74:75], v[98:99], v[54:55], v[74:75] op_sel:[1,1,0] op_sel_hi:[1,0,1] neg_lo:[1,0,0]
	ds_write_b64 v114, v[74:75]
	v_pk_mul_f32 v[74:75], v[84:85], v[56:57] op_sel:[0,0] op_sel_hi:[0,1]
	s_nop 0
	v_pk_fma_f32 v[74:75], v[84:85], v[56:57], v[74:75] op_sel:[1,1,0] op_sel_hi:[1,0,1] neg_lo:[1,0,0]
	ds_write_b64 v115, v[74:75]
	v_pk_mul_f32 v[74:75], v[86:87], v[58:59] op_sel:[0,0] op_sel_hi:[0,1]
	s_nop 0
	v_pk_fma_f32 v[74:75], v[86:87], v[58:59], v[74:75] op_sel:[1,1,0] op_sel_hi:[1,0,1] neg_lo:[1,0,0]
	ds_write_b64 v125, v[74:75]
	v_pk_mul_f32 v[74:75], v[72:73], v[60:61] op_sel:[0,0] op_sel_hi:[0,1]
	s_nop 0
	v_pk_fma_f32 v[72:73], v[72:73], v[60:61], v[74:75] op_sel:[1,1,0] op_sel_hi:[1,0,1] neg_lo:[1,0,0]
	ds_write_b64 v182, v[72:73]
	v_pk_mul_f32 v[72:73], v[82:83], v[62:63] op_sel:[0,0] op_sel_hi:[0,1]
	s_nop 0
	v_pk_fma_f32 v[72:73], v[82:83], v[62:63], v[72:73] op_sel:[1,1,0] op_sel_hi:[1,0,1] neg_lo:[1,0,0]
	ds_write_b64 v183, v[72:73]
	v_pk_mul_f32 v[72:73], v[88:89], v[64:65] op_sel:[0,0] op_sel_hi:[0,1]
	s_nop 0
	v_pk_fma_f32 v[72:73], v[88:89], v[64:65], v[72:73] op_sel:[1,1,0] op_sel_hi:[1,0,1] neg_lo:[1,0,0]
	ds_write_b64 v216, v[72:73]
	v_pk_mul_f32 v[72:73], v[78:79], v[66:67] op_sel:[0,0] op_sel_hi:[0,1]
	s_nop 0
	v_pk_fma_f32 v[72:73], v[78:79], v[66:67], v[72:73] op_sel:[1,1,0] op_sel_hi:[1,0,1] neg_lo:[1,0,0]
	ds_write_b64 v217, v[72:73]
	v_pk_mul_f32 v[72:73], v[70:71], v[68:69] op_sel:[0,0] op_sel_hi:[0,1]
	s_nop 0
	v_pk_fma_f32 v[70:71], v[70:71], v[68:69], v[72:73] op_sel:[1,1,0] op_sel_hi:[1,0,1] neg_lo:[1,0,0]
	ds_write_b64 v29, v[70:71]
	s_cbranch_vccz .LBB0_1029

; __device__ __forceinline__ cf add_mib(cf a, cf b) { cf r; asm("v_pk_add_f32 %0, %1, %2 op_sel:[0,1] op_sel_hi:[1,0] neg_hi:[0,1]" : "=v"(r) : "v"(a), "v"(b)); return r; }
; __device__ __forceinline__ cf add_pib(cf a, cf b) { cf r; asm("v_pk_add_f32 %0, %1, %2 op_sel:[0,1] op_sel_hi:[1,0] neg_lo:[0,1]" : "=v"(r) : "v"(a), "v"(b)); return r; }
; template <bool INV, bool HALFIN = false> __device__ __forceinline__ void dft16(cf (&x)[16]) {
; #pragma unroll
;     for (int m2 = 0; m2 < 4; ++m2) {
;         if (HALFIN) { const cf a0 = x[m2], a1 = x[4 + m2]; x[m2] = a0 + a1; x[8 + m2] = a0 - a1; x[4 + m2] = add_mib(a0, a1); x[12 + m2] = add_pib(a0, a1); }
;         else dft4<INV>(x[m2], x[4 + m2], x[8 + m2], x[12 + m2]);
; template <bool INV, int LST, bool HALF = false> __device__ __forceinline__ void fft_pass16(LAS cf* z, const LAS cf* Thi, const LAS cf* Tlo, int tid) {
;     ...
;             for (int q = 0; q < 16; ++q) { cf y = z[pass_pos<LST>(base, phb, q)]; if (q) y = cmulc(y, w[q]); x[q] = y; }
;             dft16<true>(x);
.LBB0_1038:
	v_add_u32_e32 v29, s21, v169
	v_and_or_b32 v29, v29, s71, v172
	v_lshl_add_u32 v37, v29, 3, v174
	s_nop 0
	s_nop 0
	v_xor_b32_e32 v41, 0x20, v37
	v_xor_b32_e32 v108, 0x40, v37
	s_nop 0
	ds_read_b64 v[70:71], v41
	v_xor_b32_e32 v109, 0x60, v37
	ds_read_b64 v[72:73], v108
	ds_read_b64 v[74:75], v37
	ds_read_b64 v[76:77], v109
	s_waitcnt lgkmcnt(3)
	v_pk_mul_f32 v[78:79], v[70:71], v[22:23] op_sel:[0,0] op_sel_hi:[0,1] neg_hi:[0,1]
	s_nop 0
	v_pk_fma_f32 v[70:71], v[70:71], v[22:23], v[78:79] op_sel:[1,1,0] op_sel_hi:[1,0,1]
	s_waitcnt lgkmcnt(2)
	v_pk_mul_f32 v[78:79], v[72:73], v[30:31] op_sel:[0,0] op_sel_hi:[0,1] neg_hi:[0,1]
	v_xor_b32_e32 v111, 0xa0, v37
	v_pk_fma_f32 v[72:73], v[72:73], v[30:31], v[78:79] op_sel:[1,1,0] op_sel_hi:[1,0,1]
	s_waitcnt lgkmcnt(0)
	v_pk_mul_f32 v[78:79], v[76:77], v[38:39] op_sel:[0,0] op_sel_hi:[0,1] neg_hi:[0,1]
	s_nop 0
	v_pk_fma_f32 v[76:77], v[76:77], v[38:39], v[78:79] op_sel:[1,1,0] op_sel_hi:[1,0,1]
	s_nop 0
	v_xor_b32_e32 v110, 0x80, v37
	v_xor_b32_e32 v112, 0xc0, v37
	s_nop 0
	ds_read_b64 v[78:79], v110
	v_xor_b32_e32 v113, 0xe0, v37
	ds_read_b64 v[80:81], v111
	ds_read_b64 v[82:83], v112
	ds_read_b64 v[84:85], v113
	s_waitcnt lgkmcnt(3)
	v_pk_mul_f32 v[86:87], v[78:79], v[42:43] op_sel:[0,0] op_sel_hi:[0,1] neg_hi:[0,1]
	s_nop 0
	v_pk_fma_f32 v[78:79], v[78:79], v[42:43], v[86:87] op_sel:[1,1,0] op_sel_hi:[1,0,1]
	s_waitcnt lgkmcnt(2)
	v_pk_mul_f32 v[86:87], v[80:81], v[48:49] op_sel:[0,0] op_sel_hi:[0,1] neg_hi:[0,1]
	v_xor_b32_e32 v115, 0x120, v37
	v_pk_fma_f32 v[80:81], v[80:81], v[48:49], v[86:87] op_sel:[1,1,0] op_sel_hi:[1,0,1]
	s_waitcnt lgkmcnt(1)
	v_pk_mul_f32 v[86:87], v[82:83], v[50:51] op_sel:[0,0] op_sel_hi:[0,1] neg_hi:[0,1]
	s_nop 0
	v_pk_fma_f32 v[82:83], v[82:83], v[50:51], v[86:87] op_sel:[1,1,0] op_sel_hi:[1,0,1]
	s_waitcnt lgkmcnt(0)
	v_pk_mul_f32 v[86:87], v[84:85], v[52:53] op_sel:[0,0] op_sel_hi:[0,1] neg_hi:[0,1]
	v_xor_b32_e32 v125, 0x140, v37
	v_pk_fma_f32 v[84:85], v[84:85], v[52:53], v[86:87] op_sel:[1,1,0] op_sel_hi:[1,0,1]
	s_nop 0
	v_xor_b32_e32 v114, 0x100, v37
	s_nop 0
	ds_read_b64 v[86:87], v114
	v_xor_b32_e32 v182, 0x160, v37
	ds_read_b64 v[88:89], v115
	ds_read_b64 v[90:91], v125
	ds_read_b64 v[92:93], v182
	s_waitcnt lgkmcnt(3)
	v_pk_mul_f32 v[94:95], v[86:87], v[54:55] op_sel:[0,0] op_sel_hi:[0,1] neg_hi:[0,1]
	s_nop 0
	v_pk_fma_f32 v[86:87], v[86:87], v[54:55], v[94:95] op_sel:[1,1,0] op_sel_hi:[1,0,1]
	s_waitcnt lgkmcnt(2)
	v_pk_mul_f32 v[94:95], v[88:89], v[56:57] op_sel:[0,0] op_sel_hi:[0,1] neg_hi:[0,1]
	v_xor_b32_e32 v216, 0x1a0, v37
	v_pk_fma_f32 v[88:89], v[88:89], v[56:57], v[94:95] op_sel:[1,1,0] op_sel_hi:[1,0,1]
	s_waitcnt lgkmcnt(1)
	v_pk_mul_f32 v[94:95], v[90:91], v[58:59] op_sel:[0,0] op_sel_hi:[0,1] neg_hi:[0,1]
	s_nop 0
	v_pk_fma_f32 v[90:91], v[90:91], v[58:59], v[94:95] op_sel:[1,1,0] op_sel_hi:[1,0,1]
	s_waitcnt lgkmcnt(0)
	v_pk_mul_f32 v[94:95], v[92:93], v[60:61] op_sel:[0,0] op_sel_hi:[0,1] neg_hi:[0,1]
	v_xor_b32_e32 v217, 0x1c0, v37
	v_pk_fma_f32 v[92:93], v[92:93], v[60:61], v[94:95] op_sel:[1,1,0] op_sel_hi:[1,0,1]
	s_nop 0
	v_xor_b32_e32 v183, 0x180, v37
	s_nop 0
	ds_read_b64 v[94:95], v183
	v_xor_b32_e32 v29, 0x1e0, v37
	ds_read_b64 v[96:97], v216
	ds_read_b64 v[98:99], v217
	ds_read_b64 v[100:101], v29
	s_waitcnt lgkmcnt(3)
	v_pk_mul_f32 v[102:103], v[94:95], v[62:63] op_sel:[0,0] op_sel_hi:[0,1] neg_hi:[0,1]
	s_mov_b32 s46, s25
	v_pk_fma_f32 v[94:95], v[94:95], v[62:63], v[102:103] op_sel:[1,1,0] op_sel_hi:[1,0,1]
	s_waitcnt lgkmcnt(2)
	v_pk_mul_f32 v[102:103], v[96:97], v[64:65] op_sel:[0,0] op_sel_hi:[0,1] neg_hi:[0,1]
	s_mov_b32 s47, s24
	v_pk_fma_f32 v[96:97], v[96:97], v[64:65], v[102:103] op_sel:[1,1,0] op_sel_hi:[1,0,1]
	s_waitcnt lgkmcnt(1)
	v_pk_mul_f32 v[102:103], v[98:99], v[66:67] op_sel:[0,0] op_sel_hi:[0,1] neg_hi:[0,1]
	s_andn2_b64 vcc, exec, s[44:45]
	v_pk_fma_f32 v[98:99], v[98:99], v[66:67], v[102:103] op_sel:[1,1,0] op_sel_hi:[1,0,1]
	s_waitcnt lgkmcnt(0)
; __device__ __forceinline__ cf add_mib(cf a, cf b) { cf r; asm("v_pk_add_f32 %0, %1, %2 op_sel:[0,1] op_sel_hi:[1,0] neg_hi:[0,1]" : "=v"(r) : "v"(a), "v"(b)); return r; }
; __device__ __forceinline__ cf add_pib(cf a, cf b) { cf r; asm("v_pk_add_f32 %0, %1, %2 op_sel:[0,1] op_sel_hi:[1,0] neg_lo:[0,1]" : "=v"(r) : "v"(a), "v"(b)); return r; }
; template <bool INV, bool HALFIN = false> __device__ __forceinline__ void dft16(cf (&x)[16]) {
; #pragma unroll
;     for (int m2 = 0; m2 < 4; ++m2) {
;         if (HALFIN) { const cf a0 = x[m2], a1 = x[4 + m2]; x[m2] = a0 + a1; x[8 + m2] = a0 - a1; x[4 + m2] = add_mib(a0, a1); x[12 + m2] = add_pib(a0, a1); }
;         else dft4<INV>(x[m2], x[4 + m2], x[8 + m2], x[12 + m2]);
;     }
;     constexpr float C1 = 0.9238795325112867f, S1 = 0.3826834323650898f, C2 = 0.7071067811865476f;
;     x[4 * 1 + 1] = tw16<INV>(x[5], C1, S1);  x[4 * 1 + 2] = tw16<INV>(x[6], C2, C2);   x[4 * 1 + 3] = tw16<INV>(x[7], S1, C1);
;     x[4 * 2 + 1] = tw16<INV>(x[9], C2, C2);  x[4 * 2 + 2] = tw16<INV>(x[10], 0.f, 1.f); x[4 * 2 + 3] = tw16<INV>(x[11], -C2, C2);
;     x[4 * 3 + 1] = tw16<INV>(x[13], S1, C1); x[4 * 3 + 2] = tw16<INV>(x[14], -C2, C2); x[4 * 3 + 3] = tw16<INV>(x[15], -C1, -S1);
; #pragma unroll
;     for (int q1 = 0; q1 < 4; ++q1) dft4<INV>(x[4 * q1], x[4 * q1 + 1], x[4 * q1 + 2], x[4 * q1 + 3]);
; }
; template <bool INV, int LST, bool HALF = false> __device__ __forceinline__ void fft_pass16(LAS cf* z, const LAS cf* Thi, const LAS cf* Tlo, int tid) {
;     ...
;             for (int m = 0; m < (HALF ? 8 : 16); ++m) z[pass_pos<LST>(base, phb, m)] = x[4 * (m & 3) + (m >> 2)];
	v_pk_mul_f32 v[102:103], v[100:101], v[68:69] op_sel:[0,0] op_sel_hi:[0,1] neg_hi:[0,1]
	s_mov_b64 s[44:45], 0
	v_pk_fma_f32 v[100:101], v[100:101], v[68:69], v[102:103] op_sel:[1,1,0] op_sel_hi:[1,0,1]
	v_pk_add_f32 v[102:103], v[74:75], v[86:87]
	v_pk_add_f32 v[74:75], v[74:75], v[86:87] neg_lo:[0,1] neg_hi:[0,1]
	v_pk_add_f32 v[86:87], v[78:79], v[94:95]
	v_pk_add_f32 v[78:79], v[78:79], v[94:95] neg_lo:[0,1] neg_hi:[0,1]
	v_pk_add_f32 v[94:95], v[102:103], v[86:87]
	v_pk_add_f32 v[86:87], v[102:103], v[86:87] neg_lo:[0,1] neg_hi:[0,1]
	v_pk_add_f32 v[102:103], v[74:75], v[78:79] op_sel:[0,1] op_sel_hi:[1,0] neg_lo:[0,1]
	v_pk_add_f32 v[74:75], v[74:75], v[78:79] op_sel:[0,1] op_sel_hi:[1,0] neg_hi:[0,1]
	v_pk_add_f32 v[78:79], v[70:71], v[88:89]
	v_pk_add_f32 v[70:71], v[70:71], v[88:89] neg_lo:[0,1] neg_hi:[0,1]
	v_pk_add_f32 v[88:89], v[80:81], v[96:97]
	v_pk_add_f32 v[80:81], v[80:81], v[96:97] neg_lo:[0,1] neg_hi:[0,1]
	v_pk_add_f32 v[96:97], v[78:79], v[88:89]
	v_pk_add_f32 v[78:79], v[78:79], v[88:89] neg_lo:[0,1] neg_hi:[0,1]
	v_pk_add_f32 v[88:89], v[70:71], v[80:81] op_sel:[0,1] op_sel_hi:[1,0] neg_lo:[0,1]
	v_pk_add_f32 v[70:71], v[70:71], v[80:81] op_sel:[0,1] op_sel_hi:[1,0] neg_hi:[0,1]
	v_pk_add_f32 v[80:81], v[72:73], v[90:91]
	v_pk_add_f32 v[72:73], v[72:73], v[90:91] neg_lo:[0,1] neg_hi:[0,1]
	v_pk_add_f32 v[90:91], v[82:83], v[98:99]
	v_pk_add_f32 v[82:83], v[82:83], v[98:99] neg_lo:[0,1] neg_hi:[0,1]
	v_pk_add_f32 v[98:99], v[80:81], v[90:91]
	v_pk_add_f32 v[80:81], v[80:81], v[90:91] neg_lo:[0,1] neg_hi:[0,1]
	v_pk_add_f32 v[90:91], v[72:73], v[82:83] op_sel:[0,1] op_sel_hi:[1,0] neg_lo:[0,1]
	v_pk_add_f32 v[72:73], v[72:73], v[82:83] op_sel:[0,1] op_sel_hi:[1,0] neg_hi:[0,1]
	v_pk_add_f32 v[82:83], v[76:77], v[92:93]
	v_pk_add_f32 v[76:77], v[76:77], v[92:93] neg_lo:[0,1] neg_hi:[0,1]
	v_pk_add_f32 v[92:93], v[84:85], v[100:101]
	v_pk_add_f32 v[84:85], v[84:85], v[100:101] neg_lo:[0,1] neg_hi:[0,1]
	v_pk_add_f32 v[100:101], v[82:83], v[92:93]
	v_pk_add_f32 v[82:83], v[82:83], v[92:93] neg_lo:[0,1] neg_hi:[0,1]
	v_pk_add_f32 v[92:93], v[76:77], v[84:85] op_sel:[0,1] op_sel_hi:[1,0] neg_lo:[0,1]
	v_pk_add_f32 v[76:77], v[76:77], v[84:85] op_sel:[0,1] op_sel_hi:[1,0] neg_hi:[0,1]
	v_pk_mul_f32 v[84:85], v[88:89], s[22:23] op_sel_hi:[1,0]
	s_nop 0
	v_pk_fma_f32 v[104:105], v[88:89], s[20:21], v[84:85] op_sel:[0,0,1] op_sel_hi:[1,0,0] neg_lo:[0,0,1] neg_hi:[0,0,1]
	v_pk_fma_f32 v[84:85], v[88:89], s[20:21], v[84:85] op_sel:[0,0,1] op_sel_hi:[1,0,0]
	s_nop 0
	v_mov_b32_e32 v105, v85
	v_pk_mul_f32 v[84:85], v[90:91], s[24:25] op_sel_hi:[1,0]
	s_nop 0
	v_pk_fma_f32 v[88:89], v[90:91], s[24:25], v[84:85] op_sel:[0,0,1] op_sel_hi:[1,0,0] neg_lo:[0,0,1] neg_hi:[0,0,1]
	v_pk_fma_f32 v[84:85], v[90:91], s[24:25], v[84:85] op_sel_hi:[1,0,0]
	v_pk_mul_f32 v[90:91], v[92:93], s[20:21] op_sel_hi:[1,0]
	v_mov_b32_e32 v89, v85
	v_pk_fma_f32 v[106:107], v[92:93], s[22:23], v[90:91] op_sel:[0,0,1] op_sel_hi:[1,0,0] neg_lo:[0,0,1] neg_hi:[0,0,1]
	v_pk_fma_f32 v[90:91], v[92:93], s[22:23], v[90:91] op_sel:[0,0,1] op_sel_hi:[1,0,0]
	v_pk_add_f32 v[84:85], v[102:103], v[88:89]
	v_mov_b32_e32 v107, v91
	v_pk_mul_f32 v[90:91], v[78:79], s[24:25] op_sel_hi:[1,0]
	v_pk_add_f32 v[88:89], v[102:103], v[88:89] neg_lo:[0,1] neg_hi:[0,1]
	v_pk_fma_f32 v[92:93], v[78:79], s[24:25], v[90:91] op_sel:[0,0,1] op_sel_hi:[1,0,0] neg_lo:[0,0,1] neg_hi:[0,0,1]
	v_pk_fma_f32 v[78:79], v[78:79], s[24:25], v[90:91] op_sel_hi:[1,0,0]
	s_nop 0
	v_mov_b32_e32 v93, v79
	v_pk_fma_f32 v[78:79], v[80:81], 0, v[80:81] op_sel:[0,0,1] op_sel_hi:[1,0,0] neg_lo:[0,0,1] neg_hi:[0,0,1]
	v_pk_fma_f32 v[80:81], v[80:81], 0, v[80:81] op_sel:[0,0,1] op_sel_hi:[1,0,0]
	s_nop 0
	v_mul_f32_e32 v80, 0x3f3504f3, v83
	v_mov_b32_e32 v79, v81
	v_pk_fma_f32 v[80:81], v[82:83], s[46:47], v[80:81] op_sel_hi:[0,1,0] neg_lo:[0,0,1] neg_hi:[0,0,1]
	v_pk_mul_f32 v[82:83], v[70:71], s[20:21] op_sel_hi:[1,0]
	s_movk_i32 s21, 0x2000
	v_pk_fma_f32 v[90:91], v[70:71], s[22:23], v[82:83] op_sel:[0,0,1] op_sel_hi:[1,0,0] neg_lo:[0,0,1] neg_hi:[0,0,1]
	v_pk_fma_f32 v[70:71], v[70:71], s[22:23], v[82:83] op_sel:[0,0,1] op_sel_hi:[1,0,0]
	s_mov_b32 s23, s37
	v_mul_f32_e32 v70, 0x3f3504f3, v73
	v_mov_b32_e32 v91, v71
	v_pk_fma_f32 v[70:71], v[72:73], s[46:47], v[70:71] op_sel_hi:[0,1,0] neg_lo:[0,0,1] neg_hi:[0,0,1]
	s_mov_b32 s46, s37
	s_mov_b32 s47, s36
	v_pk_mul_f32 v[72:73], v[76:77], s[46:47] op_sel_hi:[0,1]
	v_pk_fma_f32 v[72:73], v[76:77], s[22:23], v[72:73] op_sel:[1,0,0]
	v_pk_add_f32 v[76:77], v[94:95], v[98:99]
	v_pk_add_f32 v[82:83], v[94:95], v[98:99] neg_lo:[0,1] neg_hi:[0,1]
	v_pk_add_f32 v[94:95], v[96:97], v[100:101]
	v_pk_add_f32 v[96:97], v[96:97], v[100:101] neg_lo:[0,1] neg_hi:[0,1]
	v_pk_add_f32 v[98:99], v[76:77], v[94:95]
	v_pk_add_f32 v[76:77], v[76:77], v[94:95] neg_lo:[0,1] neg_hi:[0,1]
	v_pk_add_f32 v[94:95], v[82:83], v[96:97] op_sel:[0,1] op_sel_hi:[1,0] neg_lo:[0,1]
	v_pk_add_f32 v[82:83], v[82:83], v[96:97] op_sel:[0,1] op_sel_hi:[1,0] neg_hi:[0,1]
	v_pk_add_f32 v[96:97], v[104:105], v[106:107]
	v_pk_add_f32 v[100:101], v[104:105], v[106:107] neg_lo:[0,1] neg_hi:[0,1]
	v_pk_add_f32 v[102:103], v[84:85], v[96:97]
	v_pk_add_f32 v[84:85], v[84:85], v[96:97] neg_lo:[0,1] neg_hi:[0,1]
	v_pk_add_f32 v[96:97], v[88:89], v[100:101] op_sel:[0,1] op_sel_hi:[1,0] neg_lo:[0,1]
	v_pk_add_f32 v[88:89], v[88:89], v[100:101] op_sel:[0,1] op_sel_hi:[1,0] neg_hi:[0,1]
	v_pk_add_f32 v[100:101], v[86:87], v[78:79]
	v_pk_add_f32 v[78:79], v[86:87], v[78:79] neg_lo:[0,1] neg_hi:[0,1]
	v_pk_add_f32 v[86:87], v[92:93], v[80:81]
	v_pk_add_f32 v[80:81], v[92:93], v[80:81] neg_lo:[0,1] neg_hi:[0,1]
	v_pk_add_f32 v[92:93], v[100:101], v[86:87]
	v_pk_add_f32 v[86:87], v[100:101], v[86:87] neg_lo:[0,1] neg_hi:[0,1]
	v_pk_add_f32 v[100:101], v[78:79], v[80:81] op_sel:[0,1] op_sel_hi:[1,0] neg_lo:[0,1]
	v_pk_add_f32 v[78:79], v[78:79], v[80:81] op_sel:[0,1] op_sel_hi:[1,0] neg_hi:[0,1]
	v_pk_add_f32 v[80:81], v[74:75], v[70:71]
	v_pk_add_f32 v[70:71], v[74:75], v[70:71] neg_lo:[0,1] neg_hi:[0,1]
	v_pk_add_f32 v[74:75], v[90:91], v[72:73]
	v_pk_add_f32 v[72:73], v[90:91], v[72:73] neg_lo:[0,1] neg_hi:[0,1]
	v_pk_add_f32 v[90:91], v[80:81], v[74:75]
	v_pk_add_f32 v[74:75], v[80:81], v[74:75] neg_lo:[0,1] neg_hi:[0,1]
	v_pk_add_f32 v[80:81], v[70:71], v[72:73] op_sel:[0,1] op_sel_hi:[1,0] neg_lo:[0,1]
	v_pk_add_f32 v[70:71], v[70:71], v[72:73] op_sel:[0,1] op_sel_hi:[1,0] neg_hi:[0,1]
	ds_write_b64 v37, v[98:99]
	ds_write_b64 v41, v[102:103]
	ds_write_b64 v108, v[92:93]
	ds_write_b64 v109, v[90:91]
	ds_write_b64 v110, v[94:95]
	ds_write_b64 v111, v[96:97]
	ds_write_b64 v112, v[100:101]
	ds_write_b64 v113, v[80:81]
	ds_write_b64 v114, v[76:77]
	ds_write_b64 v115, v[84:85]
	ds_write_b64 v125, v[86:87]
	ds_write_b64 v182, v[74:75]
	ds_write_b64 v183, v[82:83]
	ds_write_b64 v216, v[88:89]
	ds_write_b64 v217, v[78:79]
	ds_write_b64 v29, v[70:71]
	s_cbranch_vccz .LBB0_1041

; __device__ __forceinline__ cf add_mib(cf a, cf b) { cf r; asm("v_pk_add_f32 %0, %1, %2 op_sel:[0,1] op_sel_hi:[1,0] neg_hi:[0,1]" : "=v"(r) : "v"(a), "v"(b)); return r; }
; __device__ __forceinline__ cf add_pib(cf a, cf b) { cf r; asm("v_pk_add_f32 %0, %1, %2 op_sel:[0,1] op_sel_hi:[1,0] neg_lo:[0,1]" : "=v"(r) : "v"(a), "v"(b)); return r; }
; template <bool INV, bool HALFIN = false> __device__ __forceinline__ void dft16(cf (&x)[16]) {
; #pragma unroll
;     for (int m2 = 0; m2 < 4; ++m2) {
;         if (HALFIN) { const cf a0 = x[m2], a1 = x[4 + m2]; x[m2] = a0 + a1; x[8 + m2] = a0 - a1; x[4 + m2] = add_mib(a0, a1); x[12 + m2] = add_pib(a0, a1); }
;         else dft4<INV>(x[m2], x[4 + m2], x[8 + m2], x[12 + m2]);
; template <bool INV, int LST, bool HALF = false> __device__ __forceinline__ void fft_pass16(LAS cf* z, const LAS cf* Thi, const LAS cf* Tlo, int tid) {
;     ...
;             for (int q = 0; q < 16; ++q) { cf y = z[pass_pos<LST>(base, phb, q)]; if (q) y = cmulc(y, w[q]); x[q] = y; }
;             dft16<true>(x);
.LBB0_1042:
	v_add_u32_e32 v21, s21, v169
	v_and_b32_e32 v21, 0x7c00, v21
	v_or_b32_e32 v29, v21, v122
	v_lshl_add_u32 v29, v29, 3, 0
	s_nop 0
	s_nop 0
	v_xor_b32_e32 v37, 0x20, v29
	v_xor_b32_e32 v41, 0x40, v29
	s_nop 0
	ds_read_b64 v[70:71], v37 offset:512
	v_xor_b32_e32 v108, 0x60, v29
	ds_read_b64 v[72:73], v41 offset:1024
	ds_read_b64 v[74:75], v29
	ds_read_b64 v[76:77], v108 offset:1536
	s_waitcnt lgkmcnt(3)
	v_pk_mul_f32 v[78:79], v[70:71], v[22:23] op_sel:[0,0] op_sel_hi:[0,1] neg_hi:[0,1]
	s_nop 0
	v_pk_fma_f32 v[70:71], v[70:71], v[22:23], v[78:79] op_sel:[1,1,0] op_sel_hi:[1,0,1]
	s_waitcnt lgkmcnt(2)
	v_pk_mul_f32 v[78:79], v[72:73], v[30:31] op_sel:[0,0] op_sel_hi:[0,1] neg_hi:[0,1]
	v_xor_b32_e32 v110, 0xa0, v29
	v_pk_fma_f32 v[72:73], v[72:73], v[30:31], v[78:79] op_sel:[1,1,0] op_sel_hi:[1,0,1]
	s_waitcnt lgkmcnt(0)
	v_pk_mul_f32 v[78:79], v[76:77], v[38:39] op_sel:[0,0] op_sel_hi:[0,1] neg_hi:[0,1]
	s_nop 0
	v_pk_fma_f32 v[76:77], v[76:77], v[38:39], v[78:79] op_sel:[1,1,0] op_sel_hi:[1,0,1]
	s_nop 0
	v_xor_b32_e32 v109, 0x80, v29
	v_xor_b32_e32 v111, 0xc0, v29
	s_nop 0
	ds_read_b64 v[78:79], v109 offset:2048
	v_xor_b32_e32 v112, 0xe0, v29
	ds_read_b64 v[80:81], v110 offset:2560
	ds_read_b64 v[82:83], v111 offset:3072
	ds_read_b64 v[84:85], v112 offset:3584
	s_waitcnt lgkmcnt(3)
	v_pk_mul_f32 v[86:87], v[78:79], v[42:43] op_sel:[0,0] op_sel_hi:[0,1] neg_hi:[0,1]
	s_nop 0
	v_pk_fma_f32 v[78:79], v[78:79], v[42:43], v[86:87] op_sel:[1,1,0] op_sel_hi:[1,0,1]
	s_waitcnt lgkmcnt(2)
	v_pk_mul_f32 v[86:87], v[80:81], v[48:49] op_sel:[0,0] op_sel_hi:[0,1] neg_hi:[0,1]
	v_xor_b32_e32 v114, 0x120, v29
	v_pk_fma_f32 v[80:81], v[80:81], v[48:49], v[86:87] op_sel:[1,1,0] op_sel_hi:[1,0,1]
	s_waitcnt lgkmcnt(1)
	v_pk_mul_f32 v[86:87], v[82:83], v[50:51] op_sel:[0,0] op_sel_hi:[0,1] neg_hi:[0,1]
	s_nop 0
	v_pk_fma_f32 v[82:83], v[82:83], v[50:51], v[86:87] op_sel:[1,1,0] op_sel_hi:[1,0,1]
	s_waitcnt lgkmcnt(0)
	v_pk_mul_f32 v[86:87], v[84:85], v[52:53] op_sel:[0,0] op_sel_hi:[0,1] neg_hi:[0,1]
	v_xor_b32_e32 v115, 0x140, v29
	v_pk_fma_f32 v[84:85], v[84:85], v[52:53], v[86:87] op_sel:[1,1,0] op_sel_hi:[1,0,1]
	s_nop 0
	v_xor_b32_e32 v113, 0x100, v29
	s_nop 0
	ds_read_b64 v[86:87], v113 offset:4096
	v_xor_b32_e32 v125, 0x160, v29
	ds_read_b64 v[88:89], v114 offset:4608
	ds_read_b64 v[90:91], v115 offset:5120
	ds_read_b64 v[92:93], v125 offset:5632
	s_waitcnt lgkmcnt(3)
	v_pk_mul_f32 v[94:95], v[86:87], v[54:55] op_sel:[0,0] op_sel_hi:[0,1] neg_hi:[0,1]
	s_nop 0
	v_pk_fma_f32 v[86:87], v[86:87], v[54:55], v[94:95] op_sel:[1,1,0] op_sel_hi:[1,0,1]
	s_waitcnt lgkmcnt(2)
	v_pk_mul_f32 v[94:95], v[88:89], v[56:57] op_sel:[0,0] op_sel_hi:[0,1] neg_hi:[0,1]
	v_xor_b32_e32 v183, 0x1a0, v29
	v_pk_fma_f32 v[88:89], v[88:89], v[56:57], v[94:95] op_sel:[1,1,0] op_sel_hi:[1,0,1]
	s_waitcnt lgkmcnt(1)
	v_pk_mul_f32 v[94:95], v[90:91], v[58:59] op_sel:[0,0] op_sel_hi:[0,1] neg_hi:[0,1]
	s_nop 0
	v_pk_fma_f32 v[90:91], v[90:91], v[58:59], v[94:95] op_sel:[1,1,0] op_sel_hi:[1,0,1]
	s_waitcnt lgkmcnt(0)
	v_pk_mul_f32 v[94:95], v[92:93], v[60:61] op_sel:[0,0] op_sel_hi:[0,1] neg_hi:[0,1]
	v_xor_b32_e32 v216, 0x1c0, v29
	v_pk_fma_f32 v[92:93], v[92:93], v[60:61], v[94:95] op_sel:[1,1,0] op_sel_hi:[1,0,1]
	s_nop 0
	v_xor_b32_e32 v182, 0x180, v29
	s_nop 0
	ds_read_b64 v[94:95], v182 offset:6144
	v_xor_b32_e32 v21, 0x1e0, v29
	ds_read_b64 v[96:97], v183 offset:6656
	ds_read_b64 v[98:99], v216 offset:7168
	ds_read_b64 v[100:101], v21 offset:7680
	s_waitcnt lgkmcnt(3)
	v_pk_mul_f32 v[102:103], v[94:95], v[62:63] op_sel:[0,0] op_sel_hi:[0,1] neg_hi:[0,1]
	s_mov_b32 s46, s25
	v_pk_fma_f32 v[94:95], v[94:95], v[62:63], v[102:103] op_sel:[1,1,0] op_sel_hi:[1,0,1]
	s_waitcnt lgkmcnt(2)
	v_pk_mul_f32 v[102:103], v[96:97], v[64:65] op_sel:[0,0] op_sel_hi:[0,1] neg_hi:[0,1]
	s_mov_b32 s47, s24
	v_pk_fma_f32 v[96:97], v[96:97], v[64:65], v[102:103] op_sel:[1,1,0] op_sel_hi:[1,0,1]
	s_waitcnt lgkmcnt(1)
	v_pk_mul_f32 v[102:103], v[98:99], v[66:67] op_sel:[0,0] op_sel_hi:[0,1] neg_hi:[0,1]
	s_andn2_b64 vcc, exec, s[44:45]
	v_pk_fma_f32 v[98:99], v[98:99], v[66:67], v[102:103] op_sel:[1,1,0] op_sel_hi:[1,0,1]
	s_waitcnt lgkmcnt(0)
	v_pk_mul_f32 v[102:103], v[100:101], v[68:69] op_sel:[0,0] op_sel_hi:[0,1] neg_hi:[0,1]
	s_mov_b64 s[44:45], 0
	v_pk_fma_f32 v[100:101], v[100:101], v[68:69], v[102:103] op_sel:[1,1,0] op_sel_hi:[1,0,1]
	v_pk_add_f32 v[102:103], v[74:75], v[86:87]
	v_pk_add_f32 v[74:75], v[74:75], v[86:87] neg_lo:[0,1] neg_hi:[0,1]
	v_pk_add_f32 v[86:87], v[78:79], v[94:95]
	v_pk_add_f32 v[78:79], v[78:79], v[94:95] neg_lo:[0,1] neg_hi:[0,1]
	v_pk_add_f32 v[94:95], v[102:103], v[86:87]
	v_pk_add_f32 v[86:87], v[102:103], v[86:87] neg_lo:[0,1] neg_hi:[0,1]
	v_pk_add_f32 v[102:103], v[74:75], v[78:79] op_sel:[0,1] op_sel_hi:[1,0] neg_lo:[0,1]
	v_pk_add_f32 v[74:75], v[74:75], v[78:79] op_sel:[0,1] op_sel_hi:[1,0] neg_hi:[0,1]
	v_pk_add_f32 v[78:79], v[70:71], v[88:89]
	v_pk_add_f32 v[70:71], v[70:71], v[88:89] neg_lo:[0,1] neg_hi:[0,1]
	v_pk_add_f32 v[88:89], v[80:81], v[96:97]
	v_pk_add_f32 v[80:81], v[80:81], v[96:97] neg_lo:[0,1] neg_hi:[0,1]
	v_pk_add_f32 v[96:97], v[78:79], v[88:89]
	v_pk_add_f32 v[78:79], v[78:79], v[88:89] neg_lo:[0,1] neg_hi:[0,1]
	v_pk_add_f32 v[88:89], v[70:71], v[80:81] op_sel:[0,1] op_sel_hi:[1,0] neg_lo:[0,1]
	v_pk_add_f32 v[70:71], v[70:71], v[80:81] op_sel:[0,1] op_sel_hi:[1,0] neg_hi:[0,1]
	v_pk_add_f32 v[80:81], v[72:73], v[90:91]
	v_pk_add_f32 v[72:73], v[72:73], v[90:91] neg_lo:[0,1] neg_hi:[0,1]
	v_pk_add_f32 v[90:91], v[82:83], v[98:99]
	v_pk_add_f32 v[82:83], v[82:83], v[98:99] neg_lo:[0,1] neg_hi:[0,1]
; __device__ __forceinline__ cf add_mib(cf a, cf b) { cf r; asm("v_pk_add_f32 %0, %1, %2 op_sel:[0,1] op_sel_hi:[1,0] neg_hi:[0,1]" : "=v"(r) : "v"(a), "v"(b)); return r; }
; __device__ __forceinline__ cf add_pib(cf a, cf b) { cf r; asm("v_pk_add_f32 %0, %1, %2 op_sel:[0,1] op_sel_hi:[1,0] neg_lo:[0,1]" : "=v"(r) : "v"(a), "v"(b)); return r; }
; template <bool INV, bool HALFIN = false> __device__ __forceinline__ void dft16(cf (&x)[16]) {
; #pragma unroll
;     for (int m2 = 0; m2 < 4; ++m2) {
;         if (HALFIN) { const cf a0 = x[m2], a1 = x[4 + m2]; x[m2] = a0 + a1; x[8 + m2] = a0 - a1; x[4 + m2] = add_mib(a0, a1); x[12 + m2] = add_pib(a0, a1); }
;         else dft4<INV>(x[m2], x[4 + m2], x[8 + m2], x[12 + m2]);
;     }
;     constexpr float C1 = 0.9238795325112867f, S1 = 0.3826834323650898f, C2 = 0.7071067811865476f;
;     x[4 * 1 + 1] = tw16<INV>(x[5], C1, S1);  x[4 * 1 + 2] = tw16<INV>(x[6], C2, C2);   x[4 * 1 + 3] = tw16<INV>(x[7], S1, C1);
;     x[4 * 2 + 1] = tw16<INV>(x[9], C2, C2);  x[4 * 2 + 2] = tw16<INV>(x[10], 0.f, 1.f); x[4 * 2 + 3] = tw16<INV>(x[11], -C2, C2);
;     x[4 * 3 + 1] = tw16<INV>(x[13], S1, C1); x[4 * 3 + 2] = tw16<INV>(x[14], -C2, C2); x[4 * 3 + 3] = tw16<INV>(x[15], -C1, -S1);
; #pragma unroll
;     for (int q1 = 0; q1 < 4; ++q1) dft4<INV>(x[4 * q1], x[4 * q1 + 1], x[4 * q1 + 2], x[4 * q1 + 3]);
; }
; template <bool INV, int LST, bool HALF = false> __device__ __forceinline__ void fft_pass16(LAS cf* z, const LAS cf* Thi, const LAS cf* Tlo, int tid) {
;     ...
;             for (int m = 0; m < (HALF ? 8 : 16); ++m) z[pass_pos<LST>(base, phb, m)] = x[4 * (m & 3) + (m >> 2)];
	v_pk_add_f32 v[98:99], v[80:81], v[90:91]
	v_pk_add_f32 v[80:81], v[80:81], v[90:91] neg_lo:[0,1] neg_hi:[0,1]
	v_pk_add_f32 v[90:91], v[72:73], v[82:83] op_sel:[0,1] op_sel_hi:[1,0] neg_lo:[0,1]
	v_pk_add_f32 v[72:73], v[72:73], v[82:83] op_sel:[0,1] op_sel_hi:[1,0] neg_hi:[0,1]
	v_pk_add_f32 v[82:83], v[76:77], v[92:93]
	v_pk_add_f32 v[76:77], v[76:77], v[92:93] neg_lo:[0,1] neg_hi:[0,1]
	v_pk_add_f32 v[92:93], v[84:85], v[100:101]
	v_pk_add_f32 v[84:85], v[84:85], v[100:101] neg_lo:[0,1] neg_hi:[0,1]
	v_pk_add_f32 v[100:101], v[82:83], v[92:93]
	v_pk_add_f32 v[82:83], v[82:83], v[92:93] neg_lo:[0,1] neg_hi:[0,1]
	v_pk_add_f32 v[92:93], v[76:77], v[84:85] op_sel:[0,1] op_sel_hi:[1,0] neg_lo:[0,1]
	v_pk_add_f32 v[76:77], v[76:77], v[84:85] op_sel:[0,1] op_sel_hi:[1,0] neg_hi:[0,1]
	v_pk_mul_f32 v[84:85], v[88:89], s[22:23] op_sel_hi:[1,0]
	s_nop 0
	v_pk_fma_f32 v[104:105], v[88:89], s[20:21], v[84:85] op_sel:[0,0,1] op_sel_hi:[1,0,0] neg_lo:[0,0,1] neg_hi:[0,0,1]
	v_pk_fma_f32 v[84:85], v[88:89], s[20:21], v[84:85] op_sel:[0,0,1] op_sel_hi:[1,0,0]
	s_nop 0
	v_mov_b32_e32 v105, v85
	v_pk_mul_f32 v[84:85], v[90:91], s[24:25] op_sel_hi:[1,0]
	s_nop 0
	v_pk_fma_f32 v[88:89], v[90:91], s[24:25], v[84:85] op_sel:[0,0,1] op_sel_hi:[1,0,0] neg_lo:[0,0,1] neg_hi:[0,0,1]
	v_pk_fma_f32 v[84:85], v[90:91], s[24:25], v[84:85] op_sel_hi:[1,0,0]
	v_pk_mul_f32 v[90:91], v[92:93], s[20:21] op_sel_hi:[1,0]
	v_mov_b32_e32 v89, v85
	v_pk_fma_f32 v[106:107], v[92:93], s[22:23], v[90:91] op_sel:[0,0,1] op_sel_hi:[1,0,0] neg_lo:[0,0,1] neg_hi:[0,0,1]
	v_pk_fma_f32 v[90:91], v[92:93], s[22:23], v[90:91] op_sel:[0,0,1] op_sel_hi:[1,0,0]
	v_pk_add_f32 v[84:85], v[102:103], v[88:89]
	v_mov_b32_e32 v107, v91
	v_pk_mul_f32 v[90:91], v[78:79], s[24:25] op_sel_hi:[1,0]
	v_pk_add_f32 v[88:89], v[102:103], v[88:89] neg_lo:[0,1] neg_hi:[0,1]
	v_pk_fma_f32 v[92:93], v[78:79], s[24:25], v[90:91] op_sel:[0,0,1] op_sel_hi:[1,0,0] neg_lo:[0,0,1] neg_hi:[0,0,1]
	v_pk_fma_f32 v[78:79], v[78:79], s[24:25], v[90:91] op_sel_hi:[1,0,0]
	s_nop 0
	v_mov_b32_e32 v93, v79
	v_pk_fma_f32 v[78:79], v[80:81], 0, v[80:81] op_sel:[0,0,1] op_sel_hi:[1,0,0] neg_lo:[0,0,1] neg_hi:[0,0,1]
	v_pk_fma_f32 v[80:81], v[80:81], 0, v[80:81] op_sel:[0,0,1] op_sel_hi:[1,0,0]
	s_nop 0
	v_mul_f32_e32 v80, 0x3f3504f3, v83
	v_mov_b32_e32 v79, v81
	v_pk_fma_f32 v[80:81], v[82:83], s[46:47], v[80:81] op_sel_hi:[0,1,0] neg_lo:[0,0,1] neg_hi:[0,0,1]
	v_pk_mul_f32 v[82:83], v[70:71], s[20:21] op_sel_hi:[1,0]
	s_movk_i32 s21, 0x2000
	v_pk_fma_f32 v[90:91], v[70:71], s[22:23], v[82:83] op_sel:[0,0,1] op_sel_hi:[1,0,0] neg_lo:[0,0,1] neg_hi:[0,0,1]
	v_pk_fma_f32 v[70:71], v[70:71], s[22:23], v[82:83] op_sel:[0,0,1] op_sel_hi:[1,0,0]
	s_mov_b32 s23, s37
	v_mul_f32_e32 v70, 0x3f3504f3, v73
	v_mov_b32_e32 v91, v71
	v_pk_fma_f32 v[70:71], v[72:73], s[46:47], v[70:71] op_sel_hi:[0,1,0] neg_lo:[0,0,1] neg_hi:[0,0,1]
	s_mov_b32 s46, s37
	s_mov_b32 s47, s36
	v_pk_mul_f32 v[72:73], v[76:77], s[46:47] op_sel_hi:[0,1]
	v_pk_fma_f32 v[72:73], v[76:77], s[22:23], v[72:73] op_sel:[1,0,0]
	v_pk_add_f32 v[76:77], v[94:95], v[98:99]
	v_pk_add_f32 v[82:83], v[94:95], v[98:99] neg_lo:[0,1] neg_hi:[0,1]
	v_pk_add_f32 v[94:95], v[96:97], v[100:101]
	v_pk_add_f32 v[96:97], v[96:97], v[100:101] neg_lo:[0,1] neg_hi:[0,1]
	v_pk_add_f32 v[98:99], v[76:77], v[94:95]
	v_pk_add_f32 v[76:77], v[76:77], v[94:95] neg_lo:[0,1] neg_hi:[0,1]
	v_pk_add_f32 v[94:95], v[82:83], v[96:97] op_sel:[0,1] op_sel_hi:[1,0] neg_lo:[0,1]
	v_pk_add_f32 v[82:83], v[82:83], v[96:97] op_sel:[0,1] op_sel_hi:[1,0] neg_hi:[0,1]
	v_pk_add_f32 v[96:97], v[104:105], v[106:107]
	v_pk_add_f32 v[100:101], v[104:105], v[106:107] neg_lo:[0,1] neg_hi:[0,1]
	v_pk_add_f32 v[102:103], v[84:85], v[96:97]
	v_pk_add_f32 v[84:85], v[84:85], v[96:97] neg_lo:[0,1] neg_hi:[0,1]
	v_pk_add_f32 v[96:97], v[88:89], v[100:101] op_sel:[0,1] op_sel_hi:[1,0] neg_lo:[0,1]
	v_pk_add_f32 v[88:89], v[88:89], v[100:101] op_sel:[0,1] op_sel_hi:[1,0] neg_hi:[0,1]
	v_pk_add_f32 v[100:101], v[86:87], v[78:79]
	v_pk_add_f32 v[78:79], v[86:87], v[78:79] neg_lo:[0,1] neg_hi:[0,1]
	v_pk_add_f32 v[86:87], v[92:93], v[80:81]
	v_pk_add_f32 v[80:81], v[92:93], v[80:81] neg_lo:[0,1] neg_hi:[0,1]
	v_pk_add_f32 v[92:93], v[100:101], v[86:87]
	v_pk_add_f32 v[86:87], v[100:101], v[86:87] neg_lo:[0,1] neg_hi:[0,1]
	v_pk_add_f32 v[100:101], v[78:79], v[80:81] op_sel:[0,1] op_sel_hi:[1,0] neg_lo:[0,1]
	v_pk_add_f32 v[78:79], v[78:79], v[80:81] op_sel:[0,1] op_sel_hi:[1,0] neg_hi:[0,1]
	v_pk_add_f32 v[80:81], v[74:75], v[70:71]
	v_pk_add_f32 v[70:71], v[74:75], v[70:71] neg_lo:[0,1] neg_hi:[0,1]
	v_pk_add_f32 v[74:75], v[90:91], v[72:73]
	v_pk_add_f32 v[72:73], v[90:91], v[72:73] neg_lo:[0,1] neg_hi:[0,1]
	v_pk_add_f32 v[90:91], v[80:81], v[74:75]
	v_pk_add_f32 v[74:75], v[80:81], v[74:75] neg_lo:[0,1] neg_hi:[0,1]
	v_pk_add_f32 v[80:81], v[70:71], v[72:73] op_sel:[0,1] op_sel_hi:[1,0] neg_lo:[0,1]
	v_pk_add_f32 v[70:71], v[70:71], v[72:73] op_sel:[0,1] op_sel_hi:[1,0] neg_hi:[0,1]
	ds_write_b64 v29, v[98:99]
	ds_write_b64 v37, v[102:103] offset:512
	ds_write_b64 v41, v[92:93] offset:1024
	ds_write_b64 v108, v[90:91] offset:1536
	ds_write_b64 v109, v[94:95] offset:2048
	ds_write_b64 v110, v[96:97] offset:2560
	ds_write_b64 v111, v[100:101] offset:3072
	ds_write_b64 v112, v[80:81] offset:3584
	ds_write_b64 v113, v[76:77] offset:4096
	ds_write_b64 v114, v[84:85] offset:4608
	ds_write_b64 v115, v[86:87] offset:5120
	ds_write_b64 v125, v[74:75] offset:5632
	ds_write_b64 v182, v[82:83] offset:6144
	ds_write_b64 v183, v[88:89] offset:6656
	ds_write_b64 v216, v[78:79] offset:7168
	ds_write_b64 v21, v[70:71] offset:7680
	s_cbranch_vccz .LBB0_1045
